# v027 plus in-loop LDS-DMA blocks without m0 save/restore
# baseline (speedup 1.0000x reference)
; __device__ __forceinline__ void glds16(const void* gsrc, unsigned lds_dst) { unsigned keep;
;     asm volatile("s_mov_b32 %0, m0\n\ts_mov_b32 m0, %2\n\ts_nop 0\n\tglobal_load_lds_dwordx4 %1, off\n\ts_mov_b32 m0, %0" : "=&s"(keep) : "v"(gsrc), "s"(lds_dst) : "memory"); }
.LBB0_704:
	s_cmp_ge_i32 s95, s85
	s_mov_b32 s96, s24
	s_cselect_b64 s[24:25], -1, 0
	s_and_b64 vcc, exec, s[24:25]
	s_cbranch_vccnz .LBB0_706
	v_lshl_add_u64 v[4:5], s[22:23], 0, v[146:147]
	s_add_i32 s26, s8, s96
	s_mov_b32 m0, s26
	s_nop 0
	global_load_lds_dwordx4 v[4:5], off
	v_lshl_add_u64 v[2:3], s[22:23], 0, v[148:149]
	s_addk_i32 s26, 0x400
	s_mov_b32 m0, s26
	s_nop 0
	global_load_lds_dwordx4 v[2:3], off
.LBB0_706:
	s_add_i32 s97, s95, 1
	s_cmp_ge_i32 s97, s86
	s_cselect_b64 s[26:27], -1, 0
	s_and_b64 vcc, exec, s[26:27]
	s_cbranch_vccnz .LBB0_708
	s_add_u32 s28, s22, 0x1fe0000
	s_addc_u32 s29, s23, 0
	v_lshl_add_u64 v[2:3], s[28:29], 0, v[152:153]
	v_lshl_add_u64 v[4:5], s[28:29], 0, v[150:151]
	s_add_i32 s28, s92, s94
	s_mov_b32 m0, s28
	s_nop 0
	global_load_lds_dwordx4 v[4:5], off
	s_addk_i32 s28, 0x400
	s_mov_b32 m0, s28
	s_nop 0
	global_load_lds_dwordx4 v[2:3], off

; __device__ __forceinline__ void glds16(const void* gsrc, unsigned lds_dst) { unsigned keep;
;     asm volatile("s_mov_b32 %0, m0\n\ts_mov_b32 m0, %2\n\ts_nop 0\n\tglobal_load_lds_dwordx4 %1, off\n\ts_mov_b32 m0, %0" : "=&s"(keep) : "v"(gsrc), "s"(lds_dst) : "memory"); }
.LBB0_735:
	s_cmp_ge_i32 s31, s85
	s_mov_b32 s92, s22
	s_cselect_b64 s[22:23], -1, 0
	s_and_b64 vcc, exec, s[22:23]
	s_cbranch_vccnz .LBB0_737
	v_lshl_add_u64 v[4:5], s[6:7], 0, v[146:147]
	s_add_i32 s24, s8, s92
	s_mov_b32 m0, s24
	s_nop 0
	global_load_lds_dwordx4 v[4:5], off
	v_lshl_add_u64 v[2:3], s[6:7], 0, v[148:149]
	s_addk_i32 s24, 0x400
	s_mov_b32 m0, s24
	s_nop 0
	global_load_lds_dwordx4 v[2:3], off
.LBB0_737:
	s_add_i32 s93, s31, 1
	s_cmp_ge_i32 s93, s86
	s_cselect_b64 s[24:25], -1, 0
	s_and_b64 vcc, exec, s[24:25]
	s_cbranch_vccnz .LBB0_739
	s_add_u32 s26, s6, 0x1fe0000
	s_addc_u32 s27, s7, 0
	v_lshl_add_u64 v[2:3], s[26:27], 0, v[152:153]
	v_lshl_add_u64 v[4:5], s[26:27], 0, v[150:151]
	s_add_i32 s26, s28, s30
	s_mov_b32 m0, s26
	s_nop 0
	global_load_lds_dwordx4 v[4:5], off
	s_addk_i32 s26, 0x400
	s_mov_b32 m0, s26
	s_nop 0
	global_load_lds_dwordx4 v[2:3], off
